# GroupNorm loop: loop-invariant weight and bias loads hoisted out of the item loop, on top of the merged recurrence-scale load (13 loads per item instead of 18)
# baseline (speedup 1.0000x reference)
; __device__ __forceinline__ f32x4 bf4(v2u u) { return (f32x4){bflo(u.x), bfhi(u.x), bflo(u.y), bfhi(u.y)}; }
; __device__ __forceinline__ void p3_gn_chunk(const Args& a, int ch, int lane) {
;     const int n = lane & 15, rg = lane >> 4, head = ch & 15, c0 = head * 64 + 4 * n; const int t0 = (ch >> 4) * 16 + 4 * rg;
;     const bf16* YR = (const bf16*)(a.ws + WS_YR); const bf16* ZB = (const bf16*)(a.ws + WS_ZB); bf16* Y = (bf16*)(a.ws + WS_XN); const float* RK = (const float*)(a.ws + WS_RK);
;     const f32x4 lw = ld4(a.in[16] + c0), lb = ld4(a.in[17] + c0);
;     f32x4 vimg[4];
; #pragma unroll
;     for (int cb = 0; cb < 4; ++cb) vimg[cb] = bf4(*(const v2u*)(a.ws + WS_VS + (size_t)ch * 2048 + cb * 512 + lane * 8));
; #pragma unroll
;     for (int e = 0; e < 4; ++e) { const int t = t0 + e;
;         f32x4 y = bf4(*(const v2u*)(YR + (size_t)t * 1024 + c0));
;         const f32x4 g = bf4(*(const v2u*)(ZB + (size_t)t * 5120 + 4096 + c0)); const float rk = RK[(size_t)t * 16 + head];
; __global__ void __launch_bounds__(NTHR, 2) hybrid_fwd(Args args) {
;     ...
;     for (int ch = F.gw; ch < (T / 16) * NH; ch += F.NGW) p3_gn_chunk(args, ch, F.lane);
.LBB0_638:
	s_or_b64 exec, exec, s[0:1]
	v_readlane_b32 s0, v254, 39
	v_readlane_b32 s1, v254, 40
	v_readlane_b32 s60, v254, 36
	v_readlane_b32 s12, v254, 6
	s_waitcnt lgkmcnt(0)
	s_barrier
	v_mbcnt_lo_u32_b32 v0, -1, 0
	v_mbcnt_hi_u32_b32 v0, -1, v0
	s_and_b64 vcc, exec, s[0:1]
	v_readlane_b32 s61, v254, 37
	v_readlane_b32 s13, v254, 7
	v_readlane_b32 s14, v254, 8
	v_readlane_b32 s15, v254, 9
	v_readlane_b32 s24, v254, 18
	v_readlane_b32 s25, v254, 19
	v_readlane_b32 s26, v254, 20
	v_readlane_b32 s27, v254, 21
	v_readlane_b32 s16, v254, 10
	v_readlane_b32 s17, v254, 11
	v_readlane_b32 s18, v254, 12
	v_readlane_b32 s19, v254, 13
	v_readlane_b32 s20, v254, 14
	v_readlane_b32 s21, v254, 15
	v_readlane_b32 s22, v254, 16
	v_readlane_b32 s23, v254, 17
	s_cbranch_vccnz .LBB0_641
	s_add_u32 s2, s90, 0x3d00000
	s_addc_u32 s3, s91, 0
	s_ashr_i32 s65, s64, 31
	v_lshlrev_b32_e32 v1, 2, v0
	s_lshl_b64 s[0:1], s[64:65], 11
	v_and_b32_e32 v30, 60, v1
	v_ashrrev_i32_e32 v1, 2, v0
	v_lshlrev_b32_e32 v0, 3, v0
	s_add_u32 s0, s90, s0
	v_and_b32_e32 v31, -4, v1
	v_ashrrev_i32_e32 v1, 31, v0
	s_addc_u32 s1, s91, s1
	v_lshl_add_u64 v[130:131], s[72:73], 0, v[0:1]
	s_mov_b32 s98, 0x05040100
	s_mov_b32 s99, 0x07060302
	s_mov_b32 s101, 0
	v_lshl_add_u64 v[0:1], s[0:1], 0, v[0:1]
	s_mov_b64 s[0:1], 0x1d000000
	s_ashr_i32 s43, s42, 31
	v_lshl_add_u64 v[8:9], v[0:1], 0, s[0:1]
	s_lshl_b64 s[0:1], s[42:43], 11
	v_mov_b32_e32 v11, 0
	s_movk_i32 s6, 0x2800
	v_mov_b64_e32 v[12:13], s[90:91]
	s_mov_b32 s7, 0xf002000
	v_mov_b32_e32 v32, 0x3a27c5ac
	s_mov_b32 s8, s64
	s_and_b32 s4, s8, 15
	v_lshl_or_b32 v0, s4, 6, v30
	v_lshlrev_b32_e32 v23, 2, v0
	global_load_dwordx4 v[134:137], v23, s[12:13]
	global_load_dwordx4 v[138:141], v23, s[14:15]
.LBB0_640:
	s_lshl_b32 s100, s8, 11
	v_lshl_add_u64 v[128:129], s[100:101], 0, v[130:131]
	s_and_b32 s4, s8, 15
	s_and_b32 s5, s8, -16
	v_lshl_or_b32 v0, s4, 6, v30
	v_add_u32_e32 v26, s5, v31
	s_lshl_b32 s4, s4, 2
	v_lshlrev_b32_e32 v10, 1, v0
	v_ashrrev_i32_e32 v27, 31, v26
	v_mad_i64_i32 v[28:29], s[10:11], v26, s6, v[12:13]
	s_add_u32 s4, s2, s4
	v_or_b32_e32 v34, 1, v26
	v_or_b32_e32 v36, 2, v26
	v_or_b32_e32 v22, 3, v26
	v_lshl_add_u64 v[38:39], s[72:73], 0, v[10:11]
	v_lshlrev_b64 v[40:41], 11, v[26:27]
	v_lshl_add_u64 v[28:29], v[28:29], 0, v[10:11]
	v_lshlrev_b32_e32 v23, 2, v0
	s_addc_u32 s5, s3, 0
	v_lshlrev_b64 v[42:43], 6, v[26:27]
	v_mad_i64_i32 v[44:45], s[10:11], v34, s6, v[12:13]
	v_mad_i64_i32 v[46:47], s[10:11], v36, s6, v[12:13]
	v_mad_i64_i32 v[48:49], s[10:11], v22, s6, v[12:13]
	v_lshl_add_u64 v[40:41], v[38:39], 0, v[40:41]
	v_add_co_u32_e32 v28, vcc, s7, v28
	global_load_dwordx2 v[14:15], v[8:9], off
	global_load_dwordx2 v[16:17], v[8:9], off offset:512
	global_load_dwordx2 v[18:19], v[8:9], off offset:1024
	global_load_dwordx2 v[20:21], v[8:9], off offset:1536
	s_nop 0
	s_nop 0
	v_lshl_add_u64 v[24:25], s[60:61], 0, v[10:11]
	v_addc_co_u32_e32 v29, vcc, 0, v29, vcc
	v_lshl_add_u64 v[42:43], s[4:5], 0, v[42:43]
	v_lshl_add_u64 v[44:45], v[44:45], 0, v[10:11]
	v_lshl_add_u64 v[46:47], v[46:47], 0, v[10:11]
	v_lshl_add_u64 v[48:49], v[48:49], 0, v[10:11]
	global_load_dwordx2 v[120:121], v[128:129], off
	global_load_dwordx2 v[122:123], v[128:129], off offset:512
	global_load_dwordx2 v[124:125], v[128:129], off offset:1024
	global_load_dwordx2 v[126:127], v[128:129], off offset:1536
	s_nop 0
	global_load_dwordx2 v[60:61], v[28:29], off
	v_bfe_u32 v117, v30, 2, 2
	v_add_lshl_u32 v117, v26, v117, 6
	global_load_dword v133, v117, s[4:5]
	v_ashrrev_i32_e32 v35, 31, v34
	v_ashrrev_i32_e32 v37, 31, v36
	v_lshlrev_b64 v[50:51], 11, v[34:35]
	v_lshlrev_b64 v[52:53], 6, v[34:35]
	v_lshlrev_b64 v[54:55], 11, v[36:37]
	v_lshlrev_b64 v[56:57], 6, v[36:37]
	v_add_co_u32_e32 v42, vcc, s7, v44
	v_lshl_add_u64 v[28:29], v[38:39], 0, v[50:51]
	s_nop 0
	v_addc_co_u32_e32 v43, vcc, 0, v45, vcc
	v_lshl_add_u64 v[44:45], s[4:5], 0, v[52:53]
	v_lshl_add_u64 v[50:51], v[38:39], 0, v[54:55]
	v_lshl_add_u64 v[52:53], s[4:5], 0, v[56:57]
	v_lshlrev_b64 v[26:27], 12, v[26:27]
	v_lshl_add_u64 v[26:27], v[24:25], 0, v[26:27]
	v_lshlrev_b64 v[34:35], 12, v[34:35]
	v_lshl_add_u64 v[34:35], v[24:25], 0, v[34:35]
	v_add_co_u32_e32 v46, vcc, s7, v46
	v_ashrrev_i32_e32 v23, 31, v22
	s_nop 0
	v_addc_co_u32_e32 v47, vcc, 0, v47, vcc
	v_lshlrev_b64 v[58:59], 11, v[22:23]
	v_lshl_add_u64 v[38:39], v[38:39], 0, v[58:59]
	v_lshlrev_b64 v[36:37], 12, v[36:37]
	v_lshl_add_u64 v[36:37], v[24:25], 0, v[36:37]
	v_add_co_u32_e32 v48, vcc, s7, v48
	s_add_i32 s8, s8, s42
	s_nop 0
	v_addc_co_u32_e32 v49, vcc, 0, v49, vcc
	v_lshl_add_u64 v[8:9], v[8:9], 0, s[0:1]
	s_cmpk_gt_i32 s8, 0x3fff
	v_lshlrev_b64 v[118:119], 6, v[22:23]
	s_nop 0
	global_load_dwordx2 v[102:103], v[42:43], off
	s_nop 0
	v_lshl_add_u64 v[118:119], s[4:5], 0, v[118:119]
	s_nop 0
	global_load_dwordx2 v[108:109], v[46:47], off
	s_nop 0
	s_nop 0
	global_load_dwordx2 v[114:115], v[48:49], off
	s_nop 0
	s_waitcnt vmcnt(12)
	v_lshlrev_b32_e32 v54, 16, v14
	v_and_b32_e32 v56, 0xffff0000, v14
	s_waitcnt vmcnt(11)
	v_lshlrev_b32_e32 v55, 16, v16
	v_and_b32_e32 v57, 0xffff0000, v16
	s_waitcnt vmcnt(10)
	v_lshlrev_b32_e32 v62, 16, v18
	v_and_b32_e32 v64, 0xffff0000, v18
	s_waitcnt vmcnt(9)
	v_lshlrev_b32_e32 v63, 16, v20
	v_and_b32_e32 v65, 0xffff0000, v20
	v_lshlrev_b32_e32 v58, 16, v15
	v_lshlrev_b32_e32 v59, 16, v17
	s_waitcnt vmcnt(5)
	v_perm_b32 v40, v122, v120, s98
	v_perm_b32 v41, v126, v124, s98
	v_perm_b32 v100, v122, v120, s99
	v_perm_b32 v101, v126, v124, s99
	v_perm_b32 v106, v123, v121, s98
	v_perm_b32 v107, v127, v125, s98
	v_perm_b32 v112, v123, v121, s99
	v_perm_b32 v113, v127, v125, s99
	v_lshlrev_b32_e32 v69, 16, v41
	v_lshlrev_b32_e32 v68, 16, v40
	v_and_b32_e32 v41, 0xffff0000, v41
	v_and_b32_e32 v40, 0xffff0000, v40
	v_pk_add_f32 v[72:73], v[68:69], v[40:41]
	s_waitcnt vmcnt(4)
; __device__ __forceinline__ f32x4 bf4(v2u u) { return (f32x4){bflo(u.x), bfhi(u.x), bflo(u.y), bfhi(u.y)}; }
; __device__ __forceinline__ v2u pk4(f32x4 v) { v2u o; o.x = pk2(v.x, v.y); o.y = pk2(v.z, v.w); return o; }
; __device__ __forceinline__ void p3_gn_chunk(const Args& a, int ch, int lane) {
;     ...
;     for (int e = 0; e < 4; ++e) { const int t = t0 + e;
;         f32x4 y = bf4(*(const v2u*)(YR + (size_t)t * 1024 + c0));
;         const f32x4 g = bf4(*(const v2u*)(ZB + (size_t)t * 5120 + 4096 + c0)); const float rk = RK[(size_t)t * 16 + head];
;         const float mean = row16_sum((y.x + y.y) + (y.z + y.w)) * (1.f / 64.f);
;         y = y - mean;
;         const float rstd = __builtin_amdgcn_rsqf(row16_sum((y.x * y.x + y.y * y.y) + (y.z * y.z + y.w * y.w)) * (1.f / 64.f) + GN_EPS);
;         const f32x4 v = {vimg[0][e], vimg[1][e], vimg[2][e], vimg[3][e]};
;         f32x4 o = y * rstd * lw + lb + v * rk;
; #pragma unroll
;         for (int k = 0; k < 4; ++k) o[k] *= g[k] * __builtin_amdgcn_rcpf(1.f + __expf(-g[k]));
;         *(v2u*)(Y + (size_t)t * 2048 + c0) = pk4(o); }
	v_lshlrev_b32_e32 v70, 16, v60
	v_add_f32_e32 v33, v72, v73
	v_mul_f32_e32 v14, 0xbfb8aa3b, v70
	v_exp_f32_e32 v14, v14
	v_add_f32_dpp v33, v33, v33 quad_perm:[1,0,3,2] row_mask:0xf bank_mask:0xf bound_ctrl:1
	v_and_b32_e32 v71, 0xffff0000, v60
	v_lshlrev_b32_e32 v60, 16, v61
	v_add_f32_dpp v33, v33, v33 quad_perm:[2,3,0,1] row_mask:0xf bank_mask:0xf bound_ctrl:1
	v_add_f32_e32 v14, 1.0, v14
	v_rcp_f32_e32 v72, v14
	v_add_f32_dpp v33, v33, v33 row_half_mirror row_mask:0xf bank_mask:0xf bound_ctrl:1
	v_and_b32_e32 v61, 0xffff0000, v61
	v_mul_f32_e32 v16, 0xbfb8aa3b, v71
	v_add_f32_dpp v33, v33, v33 row_mirror row_mask:0xf bank_mask:0xf bound_ctrl:1
	v_fmac_f32_e32 v40, 0xbc800000, v33
	v_fmac_f32_e32 v41, 0xbc800000, v33
	v_fmac_f32_e32 v69, 0xbc800000, v33
	v_fmac_f32_e32 v68, 0xbc800000, v33
	v_mov_b32_e32 v76, v69
	v_mov_b32_e32 v77, v41
	v_mov_b32_e32 v69, v40
	v_pk_mul_f32 v[40:41], v[76:77], v[76:77]
	v_pk_mul_f32 v[78:79], v[68:69], v[68:69]
	v_mul_f32_e32 v18, 0xbfb8aa3b, v60
	v_pk_mov_b32 v[80:81], v[78:79], v[40:41] op_sel:[1,0]
	v_mov_b32_e32 v79, v41
	v_pk_add_f32 v[40:41], v[80:81], v[78:79]
	v_mul_f32_e32 v20, 0xbfb8aa3b, v61
	v_add_f32_e32 v14, v40, v41
	v_exp_f32_e32 v16, v16
	v_exp_f32_e32 v18, v18
	v_add_f32_dpp v14, v14, v14 quad_perm:[1,0,3,2] row_mask:0xf bank_mask:0xf bound_ctrl:1
	v_exp_f32_e32 v20, v20
	v_add_f32_e32 v16, 1.0, v16
	v_add_f32_dpp v14, v14, v14 quad_perm:[2,3,0,1] row_mask:0xf bank_mask:0xf bound_ctrl:1
	v_add_f32_e32 v18, 1.0, v18
	v_add_f32_e32 v20, 1.0, v20
	v_add_f32_dpp v14, v14, v14 row_half_mirror row_mask:0xf bank_mask:0xf bound_ctrl:1
	v_rcp_f32_e32 v73, v16
	v_rcp_f32_e32 v74, v18
	v_add_f32_dpp v14, v14, v14 row_mirror row_mask:0xf bank_mask:0xf bound_ctrl:1
	v_fmamk_f32 v14, v14, 0x3c800000, v32
	v_rsq_f32_e32 v14, v14
	v_rcp_f32_e32 v75, v20
	v_pk_mul_f32 v[70:71], v[72:73], v[70:71]
	v_lshlrev_b32_e32 v66, 16, v19
	v_pk_mul_f32 v[40:41], v[76:77], v[14:15] op_sel_hi:[1,0]
	v_pk_mul_f32 v[68:69], v[68:69], v[14:15] op_sel_hi:[1,0]
	v_pk_fma_f32 v[40:41], v[136:137], v[40:41], v[140:141]
	v_pk_fma_f32 v[68:69], v[134:135], v[68:69], v[138:139]
	v_pk_mul_f32 v[60:61], v[74:75], v[60:61]
	s_waitcnt vmcnt(3)
	v_mov_b32_dpp v10, v133 quad_perm:[0,0,0,0] row_mask:0xf bank_mask:0xf
	v_mov_b32_dpp v104, v133 quad_perm:[1,1,1,1] row_mask:0xf bank_mask:0xf
	v_mov_b32_dpp v110, v133 quad_perm:[2,2,2,2] row_mask:0xf bank_mask:0xf
	v_mov_b32_dpp v116, v133 quad_perm:[3,3,3,3] row_mask:0xf bank_mask:0xf
	s_nop 0
	v_pk_fma_f32 v[40:41], v[10:11], v[62:63], v[40:41] op_sel_hi:[0,1,1]
	v_pk_fma_f32 v[54:55], v[10:11], v[54:55], v[68:69] op_sel_hi:[0,1,1]
	v_pk_mul_f32 v[54:55], v[70:71], v[54:55]
	v_pk_mul_f32 v[40:41], v[60:61], v[40:41]
	v_cvt_pk_bf16_f32 v54, v54, v55
	v_cvt_pk_bf16_f32 v55, v40, v41
	global_store_dwordx2 v[26:27], v[54:55], off
	s_waitcnt vmcnt(1)
	v_mov_b32_e32 v26, v100
	v_mov_b32_e32 v27, v101
	v_mov_b32_e32 v28, v102
	v_mov_b32_e32 v29, v103
	v_mov_b32_e32 v10, v104
	s_nop 0
	v_lshlrev_b32_e32 v67, 16, v21
	s_nop 0
	v_lshlrev_b32_e32 v41, 16, v27
	v_lshlrev_b32_e32 v40, 16, v26
	v_and_b32_e32 v27, 0xffff0000, v27
	v_and_b32_e32 v26, 0xffff0000, v26
	v_pk_add_f32 v[44:45], v[40:41], v[26:27]
	s_nop 0
	v_lshlrev_b32_e32 v42, 16, v28
	v_add_f32_e32 v33, v44, v45
	v_mul_f32_e32 v14, 0xbfb8aa3b, v42
	v_exp_f32_e32 v14, v14
	v_add_f32_dpp v33, v33, v33 quad_perm:[1,0,3,2] row_mask:0xf bank_mask:0xf bound_ctrl:1
	v_and_b32_e32 v43, 0xffff0000, v28
	v_lshlrev_b32_e32 v28, 16, v29
	v_add_f32_dpp v33, v33, v33 quad_perm:[2,3,0,1] row_mask:0xf bank_mask:0xf bound_ctrl:1
	v_add_f32_e32 v14, 1.0, v14
	v_rcp_f32_e32 v44, v14
	v_add_f32_dpp v33, v33, v33 row_half_mirror row_mask:0xf bank_mask:0xf bound_ctrl:1
	v_and_b32_e32 v29, 0xffff0000, v29
	v_mul_f32_e32 v16, 0xbfb8aa3b, v43
	v_add_f32_dpp v33, v33, v33 row_mirror row_mask:0xf bank_mask:0xf bound_ctrl:1
	v_fmac_f32_e32 v26, 0xbc800000, v33
	v_fmac_f32_e32 v27, 0xbc800000, v33
	v_fmac_f32_e32 v41, 0xbc800000, v33
	v_fmac_f32_e32 v40, 0xbc800000, v33
	v_mov_b32_e32 v60, v41
	v_mov_b32_e32 v61, v27
	v_mov_b32_e32 v41, v26
	v_pk_mul_f32 v[26:27], v[60:61], v[60:61]
	v_pk_mul_f32 v[62:63], v[40:41], v[40:41]
	v_mul_f32_e32 v18, 0xbfb8aa3b, v28
	v_pk_mov_b32 v[68:69], v[62:63], v[26:27] op_sel:[1,0]
	v_mov_b32_e32 v63, v27
	v_pk_add_f32 v[26:27], v[68:69], v[62:63]
	v_mul_f32_e32 v20, 0xbfb8aa3b, v29
	v_add_f32_e32 v14, v26, v27
	v_exp_f32_e32 v16, v16
	v_exp_f32_e32 v18, v18
	v_add_f32_dpp v14, v14, v14 quad_perm:[1,0,3,2] row_mask:0xf bank_mask:0xf bound_ctrl:1
	v_exp_f32_e32 v20, v20
	v_add_f32_e32 v16, 1.0, v16
	v_add_f32_dpp v14, v14, v14 quad_perm:[2,3,0,1] row_mask:0xf bank_mask:0xf bound_ctrl:1
	v_add_f32_e32 v18, 1.0, v18
	v_add_f32_e32 v20, 1.0, v20
	v_add_f32_dpp v14, v14, v14 row_half_mirror row_mask:0xf bank_mask:0xf bound_ctrl:1
	v_rcp_f32_e32 v45, v16
	v_rcp_f32_e32 v54, v18
	v_add_f32_dpp v14, v14, v14 row_mirror row_mask:0xf bank_mask:0xf bound_ctrl:1
	v_fmamk_f32 v14, v14, 0x3c800000, v32
	v_rsq_f32_e32 v14, v14
	v_rcp_f32_e32 v55, v20
	v_pk_mul_f32 v[42:43], v[44:45], v[42:43]
	v_pk_mul_f32 v[26:27], v[60:61], v[14:15] op_sel_hi:[1,0]
	v_pk_mul_f32 v[40:41], v[40:41], v[14:15] op_sel_hi:[1,0]
	v_pk_fma_f32 v[26:27], v[136:137], v[26:27], v[140:141]
	v_pk_fma_f32 v[40:41], v[134:135], v[40:41], v[138:139]
	v_pk_mul_f32 v[28:29], v[54:55], v[28:29]
	s_nop 0
	v_pk_fma_f32 v[26:27], v[10:11], v[64:65], v[26:27] op_sel_hi:[0,1,1]
	v_pk_fma_f32 v[40:41], v[10:11], v[56:57], v[40:41] op_sel_hi:[0,1,1]
	v_pk_mul_f32 v[40:41], v[42:43], v[40:41]
	v_pk_mul_f32 v[26:27], v[28:29], v[26:27]
	v_cvt_pk_bf16_f32 v28, v40, v41
; __device__ __forceinline__ f32x4 bf4(v2u u) { return (f32x4){bflo(u.x), bfhi(u.x), bflo(u.y), bfhi(u.y)}; }
; __device__ __forceinline__ v2u pk4(f32x4 v) { v2u o; o.x = pk2(v.x, v.y); o.y = pk2(v.z, v.w); return o; }
; __device__ __forceinline__ void p3_gn_chunk(const Args& a, int ch, int lane) {
;     ...
;     for (int e = 0; e < 4; ++e) { const int t = t0 + e;
;         f32x4 y = bf4(*(const v2u*)(YR + (size_t)t * 1024 + c0));
;         const f32x4 g = bf4(*(const v2u*)(ZB + (size_t)t * 5120 + 4096 + c0)); const float rk = RK[(size_t)t * 16 + head];
;         const float mean = row16_sum((y.x + y.y) + (y.z + y.w)) * (1.f / 64.f);
;         y = y - mean;
;         const float rstd = __builtin_amdgcn_rsqf(row16_sum((y.x * y.x + y.y * y.y) + (y.z * y.z + y.w * y.w)) * (1.f / 64.f) + GN_EPS);
;         const f32x4 v = {vimg[0][e], vimg[1][e], vimg[2][e], vimg[3][e]};
;         f32x4 o = y * rstd * lw + lb + v * rk;
; #pragma unroll
;         for (int k = 0; k < 4; ++k) o[k] *= g[k] * __builtin_amdgcn_rcpf(1.f + __expf(-g[k]));
;         *(v2u*)(Y + (size_t)t * 2048 + c0) = pk4(o); }
	v_cvt_pk_bf16_f32 v29, v26, v27
	global_store_dwordx2 v[34:35], v[28:29], off
	s_nop 0
	v_mov_b32_e32 v26, v106
	v_mov_b32_e32 v27, v107
	v_mov_b32_e32 v28, v108
	v_mov_b32_e32 v29, v109
	v_mov_b32_e32 v10, v110
	s_nop 0
	s_nop 0
	v_lshlrev_b32_e32 v35, 16, v27
	v_lshlrev_b32_e32 v34, 16, v26
	v_and_b32_e32 v27, 0xffff0000, v27
	v_and_b32_e32 v26, 0xffff0000, v26
	v_pk_add_f32 v[42:43], v[34:35], v[26:27]
	s_nop 0
	v_lshlrev_b32_e32 v40, 16, v28
	v_add_f32_e32 v33, v42, v43
	v_mul_f32_e32 v14, 0xbfb8aa3b, v40
	v_exp_f32_e32 v14, v14
	v_add_f32_dpp v33, v33, v33 quad_perm:[1,0,3,2] row_mask:0xf bank_mask:0xf bound_ctrl:1
	v_and_b32_e32 v41, 0xffff0000, v28
	v_lshlrev_b32_e32 v28, 16, v29
	v_add_f32_dpp v33, v33, v33 quad_perm:[2,3,0,1] row_mask:0xf bank_mask:0xf bound_ctrl:1
	v_add_f32_e32 v14, 1.0, v14
	v_rcp_f32_e32 v42, v14
	v_add_f32_dpp v33, v33, v33 row_half_mirror row_mask:0xf bank_mask:0xf bound_ctrl:1
	v_and_b32_e32 v29, 0xffff0000, v29
	v_mul_f32_e32 v16, 0xbfb8aa3b, v41
	v_add_f32_dpp v33, v33, v33 row_mirror row_mask:0xf bank_mask:0xf bound_ctrl:1
	v_fmac_f32_e32 v26, 0xbc800000, v33
	v_fmac_f32_e32 v27, 0xbc800000, v33
	v_fmac_f32_e32 v35, 0xbc800000, v33
	v_fmac_f32_e32 v34, 0xbc800000, v33
	v_mov_b32_e32 v46, v35
	v_mov_b32_e32 v47, v27
	v_mov_b32_e32 v35, v26
	v_pk_mul_f32 v[26:27], v[46:47], v[46:47]
	v_pk_mul_f32 v[50:51], v[34:35], v[34:35]
	v_mul_f32_e32 v18, 0xbfb8aa3b, v28
	v_pk_mov_b32 v[52:53], v[50:51], v[26:27] op_sel:[1,0]
	v_mov_b32_e32 v51, v27
	v_pk_add_f32 v[26:27], v[52:53], v[50:51]
	v_mul_f32_e32 v20, 0xbfb8aa3b, v29
	v_add_f32_e32 v14, v26, v27
	v_exp_f32_e32 v16, v16
	v_exp_f32_e32 v18, v18
	v_add_f32_dpp v14, v14, v14 quad_perm:[1,0,3,2] row_mask:0xf bank_mask:0xf bound_ctrl:1
	v_exp_f32_e32 v20, v20
	v_add_f32_e32 v16, 1.0, v16
	v_add_f32_dpp v14, v14, v14 quad_perm:[2,3,0,1] row_mask:0xf bank_mask:0xf bound_ctrl:1
	v_add_f32_e32 v18, 1.0, v18
	v_add_f32_e32 v20, 1.0, v20
	v_add_f32_dpp v14, v14, v14 row_half_mirror row_mask:0xf bank_mask:0xf bound_ctrl:1
	v_rcp_f32_e32 v43, v16
	v_rcp_f32_e32 v44, v18
	v_add_f32_dpp v14, v14, v14 row_mirror row_mask:0xf bank_mask:0xf bound_ctrl:1
	v_fmamk_f32 v14, v14, 0x3c800000, v32
	v_rsq_f32_e32 v14, v14
	v_rcp_f32_e32 v45, v20
	v_pk_mul_f32 v[40:41], v[42:43], v[40:41]
	v_and_b32_e32 v16, 0xffff0000, v19
	v_pk_mul_f32 v[26:27], v[46:47], v[14:15] op_sel_hi:[1,0]
	v_pk_mul_f32 v[34:35], v[34:35], v[14:15] op_sel_hi:[1,0]
	v_pk_fma_f32 v[26:27], v[136:137], v[26:27], v[140:141]
	v_pk_fma_f32 v[34:35], v[134:135], v[34:35], v[138:139]
	v_pk_mul_f32 v[28:29], v[44:45], v[28:29]
	s_nop 0
	v_pk_fma_f32 v[26:27], v[10:11], v[66:67], v[26:27] op_sel_hi:[0,1,1]
	v_pk_fma_f32 v[34:35], v[10:11], v[58:59], v[34:35] op_sel_hi:[0,1,1]
	v_pk_mul_f32 v[34:35], v[40:41], v[34:35]
	v_pk_mul_f32 v[26:27], v[28:29], v[26:27]
	v_cvt_pk_bf16_f32 v28, v34, v35
	v_cvt_pk_bf16_f32 v29, v26, v27
	global_store_dwordx2 v[36:37], v[28:29], off
	s_nop 0
	v_mov_b32_e32 v26, v112
	v_mov_b32_e32 v27, v113
	v_mov_b32_e32 v28, v114
	v_mov_b32_e32 v29, v115
	v_mov_b32_e32 v10, v116
	s_nop 0
	v_lshlrev_b64 v[34:35], 6, v[22:23]
	v_lshl_add_u64 v[34:35], s[4:5], 0, v[34:35]
	v_lshlrev_b64 v[22:23], 12, v[22:23]
	v_and_b32_e32 v14, 0xffff0000, v15
	v_and_b32_e32 v15, 0xffff0000, v17
	v_and_b32_e32 v17, 0xffff0000, v21
	v_lshl_add_u64 v[22:23], v[24:25], 0, v[22:23]
	s_nop 0
	v_lshlrev_b32_e32 v19, 16, v27
	v_lshlrev_b32_e32 v18, 16, v26
	v_and_b32_e32 v21, 0xffff0000, v27
	v_and_b32_e32 v20, 0xffff0000, v26
	s_nop 0
	v_lshlrev_b32_e32 v24, 16, v28
	v_and_b32_e32 v25, 0xffff0000, v28
	v_lshlrev_b32_e32 v26, 16, v29
	v_and_b32_e32 v27, 0xffff0000, v29
	v_pk_add_f32 v[28:29], v[18:19], v[20:21]
	v_mul_f32_e32 v33, 0xbfb8aa3b, v24
	v_add_f32_e32 v28, v28, v29
	v_mul_f32_e32 v34, 0xbfb8aa3b, v25
	v_mul_f32_e32 v35, 0xbfb8aa3b, v26
	v_add_f32_dpp v28, v28, v28 quad_perm:[1,0,3,2] row_mask:0xf bank_mask:0xf bound_ctrl:1
	v_mul_f32_e32 v36, 0xbfb8aa3b, v27
	v_exp_f32_e32 v29, v33
	v_add_f32_dpp v28, v28, v28 quad_perm:[2,3,0,1] row_mask:0xf bank_mask:0xf bound_ctrl:1
	v_exp_f32_e32 v33, v34
	v_exp_f32_e32 v34, v35
	v_add_f32_dpp v28, v28, v28 row_half_mirror row_mask:0xf bank_mask:0xf bound_ctrl:1
	v_exp_f32_e32 v35, v36
	v_add_f32_e32 v29, 1.0, v29
	v_add_f32_dpp v28, v28, v28 row_mirror row_mask:0xf bank_mask:0xf bound_ctrl:1
	v_fmac_f32_e32 v20, 0xbc800000, v28
	v_fmac_f32_e32 v21, 0xbc800000, v28
	v_fmac_f32_e32 v19, 0xbc800000, v28
	v_fmac_f32_e32 v18, 0xbc800000, v28
	v_mov_b32_e32 v36, v19
	v_mov_b32_e32 v37, v21
	v_mov_b32_e32 v19, v20
	v_pk_mul_f32 v[20:21], v[36:37], v[36:37]
	v_pk_mul_f32 v[38:39], v[18:19], v[18:19]
	v_add_f32_e32 v33, 1.0, v33
	v_pk_mov_b32 v[40:41], v[38:39], v[20:21] op_sel:[1,0]
	v_mov_b32_e32 v39, v21
	v_pk_add_f32 v[20:21], v[40:41], v[38:39]
	v_rcp_f32_e32 v28, v29
	v_add_f32_e32 v20, v20, v21
	v_rcp_f32_e32 v29, v33
	v_add_f32_e32 v34, 1.0, v34
	v_add_f32_dpp v20, v20, v20 quad_perm:[1,0,3,2] row_mask:0xf bank_mask:0xf bound_ctrl:1
	v_add_f32_e32 v35, 1.0, v35
	v_rcp_f32_e32 v34, v34
	v_add_f32_dpp v20, v20, v20 quad_perm:[2,3,0,1] row_mask:0xf bank_mask:0xf bound_ctrl:1
	v_rcp_f32_e32 v35, v35
	v_pk_mul_f32 v[24:25], v[28:29], v[24:25]
	v_add_f32_dpp v20, v20, v20 row_half_mirror row_mask:0xf bank_mask:0xf bound_ctrl:1
	v_pk_mul_f32 v[26:27], v[34:35], v[26:27]
	s_nop 0
	v_add_f32_dpp v20, v20, v20 row_mirror row_mask:0xf bank_mask:0xf bound_ctrl:1
	v_fmamk_f32 v20, v20, 0x3c800000, v32
	v_rsq_f32_e32 v20, v20
	s_nop 0
	v_pk_mul_f32 v[28:29], v[36:37], v[20:21] op_sel_hi:[1,0]
	v_pk_mul_f32 v[18:19], v[18:19], v[20:21] op_sel_hi:[1,0]
	v_pk_fma_f32 v[2:3], v[136:137], v[28:29], v[140:141]
	v_pk_fma_f32 v[0:1], v[134:135], v[18:19], v[138:139]
	s_nop 0
	v_pk_fma_f32 v[2:3], v[10:11], v[16:17], v[2:3] op_sel_hi:[0,1,1]
	v_pk_fma_f32 v[0:1], v[10:11], v[14:15], v[0:1] op_sel_hi:[0,1,1]
	v_pk_mul_f32 v[0:1], v[24:25], v[0:1]
	v_pk_mul_f32 v[2:3], v[26:27], v[2:3]
	v_cvt_pk_bf16_f32 v0, v0, v1
	v_cvt_pk_bf16_f32 v1, v2, v3
	global_store_dwordx2 v[22:23], v[0:1], off
	s_cbranch_scc0 .LBB0_640
